# modulation GEMV inner loop keeps 32 weight-row loads in flight (was 4 loads then a full wait), same FMA order
# speedup vs baseline: 1.0322x; 1.0022x over previous
.LBB0_15:
	s_mov_b64 s[16:17], 0
	s_mov_b64 s[18:19], 0x9000
	s_mov_b64 s[20:21], 0x12000
	s_mov_b64 s[34:35], 0x1b000
	s_mov_b32 s38, 4
	v_lshl_add_u64 v[132:133], v[22:23], 0, s[16:17]
	v_lshl_add_u64 v[134:135], v[132:133], 0, s[18:19]
	v_lshl_add_u64 v[136:137], v[132:133], 0, s[20:21]
	v_lshl_add_u64 v[138:139], v[132:133], 0, s[34:35]
	global_load_dword v100, v[132:133], off
	global_load_dword v101, v[134:135], off
	global_load_dword v102, v[136:137], off
	global_load_dword v103, v[138:139], off
	s_add_u32 s16, s16, 0x24000
	s_cmp_eq_u32 s16, 0x480000
	s_cselect_b32 s16, 0, s16
	v_lshl_add_u64 v[132:133], v[22:23], 0, s[16:17]
	v_lshl_add_u64 v[134:135], v[132:133], 0, s[18:19]
	v_lshl_add_u64 v[136:137], v[132:133], 0, s[20:21]
	v_lshl_add_u64 v[138:139], v[132:133], 0, s[34:35]
	global_load_dword v104, v[132:133], off
	global_load_dword v105, v[134:135], off
	global_load_dword v106, v[136:137], off
	global_load_dword v107, v[138:139], off
	s_add_u32 s16, s16, 0x24000
	s_cmp_eq_u32 s16, 0x480000
	s_cselect_b32 s16, 0, s16
	v_lshl_add_u64 v[132:133], v[22:23], 0, s[16:17]
	v_lshl_add_u64 v[134:135], v[132:133], 0, s[18:19]
	v_lshl_add_u64 v[136:137], v[132:133], 0, s[20:21]
	v_lshl_add_u64 v[138:139], v[132:133], 0, s[34:35]
	global_load_dword v108, v[132:133], off
	global_load_dword v109, v[134:135], off
	global_load_dword v110, v[136:137], off
	global_load_dword v111, v[138:139], off
	s_add_u32 s16, s16, 0x24000
	s_cmp_eq_u32 s16, 0x480000
	s_cselect_b32 s16, 0, s16
	v_lshl_add_u64 v[132:133], v[22:23], 0, s[16:17]
	v_lshl_add_u64 v[134:135], v[132:133], 0, s[18:19]
	v_lshl_add_u64 v[136:137], v[132:133], 0, s[20:21]
	v_lshl_add_u64 v[138:139], v[132:133], 0, s[34:35]
	global_load_dword v112, v[132:133], off
	global_load_dword v113, v[134:135], off
	global_load_dword v114, v[136:137], off
	global_load_dword v115, v[138:139], off
	s_add_u32 s16, s16, 0x24000
	s_cmp_eq_u32 s16, 0x480000
	s_cselect_b32 s16, 0, s16
	v_lshl_add_u64 v[132:133], v[22:23], 0, s[16:17]
	v_lshl_add_u64 v[134:135], v[132:133], 0, s[18:19]
	v_lshl_add_u64 v[136:137], v[132:133], 0, s[20:21]
	v_lshl_add_u64 v[138:139], v[132:133], 0, s[34:35]
	global_load_dword v116, v[132:133], off
	global_load_dword v117, v[134:135], off
	global_load_dword v118, v[136:137], off
	global_load_dword v119, v[138:139], off
	s_add_u32 s16, s16, 0x24000
	s_cmp_eq_u32 s16, 0x480000
	s_cselect_b32 s16, 0, s16
	v_lshl_add_u64 v[132:133], v[22:23], 0, s[16:17]
	v_lshl_add_u64 v[134:135], v[132:133], 0, s[18:19]
	v_lshl_add_u64 v[136:137], v[132:133], 0, s[20:21]
	v_lshl_add_u64 v[138:139], v[132:133], 0, s[34:35]
	global_load_dword v120, v[132:133], off
	global_load_dword v121, v[134:135], off
	global_load_dword v122, v[136:137], off
	global_load_dword v123, v[138:139], off
	s_add_u32 s16, s16, 0x24000
	s_cmp_eq_u32 s16, 0x480000
	s_cselect_b32 s16, 0, s16
	v_lshl_add_u64 v[132:133], v[22:23], 0, s[16:17]
	v_lshl_add_u64 v[134:135], v[132:133], 0, s[18:19]
	v_lshl_add_u64 v[136:137], v[132:133], 0, s[20:21]
	v_lshl_add_u64 v[138:139], v[132:133], 0, s[34:35]
	global_load_dword v124, v[132:133], off
	global_load_dword v125, v[134:135], off
	global_load_dword v126, v[136:137], off
	global_load_dword v127, v[138:139], off
	s_add_u32 s16, s16, 0x24000
	s_cmp_eq_u32 s16, 0x480000
	s_cselect_b32 s16, 0, s16
	v_lshl_add_u64 v[132:133], v[22:23], 0, s[16:17]
	v_lshl_add_u64 v[134:135], v[132:133], 0, s[18:19]
	v_lshl_add_u64 v[136:137], v[132:133], 0, s[20:21]
	v_lshl_add_u64 v[138:139], v[132:133], 0, s[34:35]
	global_load_dword v128, v[132:133], off
	global_load_dword v129, v[134:135], off
	global_load_dword v130, v[136:137], off
	global_load_dword v131, v[138:139], off
	s_add_u32 s16, s16, 0x24000
	s_cmp_eq_u32 s16, 0x480000
	s_cselect_b32 s16, 0, s16
.Lpm_loop:
	ds_read_b128 v[26:29], v11 offset:4096
	ds_read_b128 v[30:33], v11 offset:8192
	ds_read_b128 v[34:37], v11 offset:12288
	ds_read_b128 v[38:41], v11 offset:16384
	ds_read_b128 v[42:45], v11 offset:20480
	ds_read_b128 v[46:49], v11 offset:24576
	ds_read_b128 v[50:53], v11 offset:28672
	ds_read_b128 v[54:57], v11
	ds_read_b128 v[58:61], v11 offset:32768
	s_waitcnt lgkmcnt(0)
	v_mov_b32_e32 v70, v34
	v_mov_b32_e32 v71, v30
	v_mov_b32_e32 v30, v35
	v_mov_b32_e32 v34, v36
	v_mov_b32_e32 v35, v32
	v_mov_b32_e32 v32, v37
	v_mov_b32_e32 v36, v42
	v_mov_b32_e32 v37, v38
	v_mov_b32_e32 v38, v43
	v_mov_b32_e32 v42, v44
	v_mov_b32_e32 v43, v40
	v_mov_b32_e32 v40, v45
	v_mov_b32_e32 v44, v50
	v_mov_b32_e32 v45, v46
	v_mov_b32_e32 v46, v51
	v_mov_b32_e32 v50, v52
	v_mov_b32_e32 v51, v48
	v_mov_b32_e32 v48, v53
	v_mov_b32_e32 v52, v54
	v_mov_b32_e32 v53, v58
	v_mov_b32_e32 v58, v55
	v_mov_b32_e32 v54, v56
	v_mov_b32_e32 v55, v60
	v_mov_b32_e32 v60, v57
	v_add_u32_e32 v11, 16, v11
	s_waitcnt vmcnt(28)
	v_mov_b32_e32 v62, v100
	v_mov_b32_e32 v64, v101
	v_mov_b32_e32 v66, v102
	v_mov_b32_e32 v68, v103
	v_fmac_f32_e32 v24, v62, v26
	v_pk_fma_f32 v[20:21], v[62:63], v[70:71], v[20:21] op_sel_hi:[0,1,1]
	v_pk_fma_f32 v[18:19], v[62:63], v[36:37], v[18:19] op_sel_hi:[0,1,1]
	v_pk_fma_f32 v[16:17], v[62:63], v[44:45], v[16:17] op_sel_hi:[0,1,1]
	v_pk_fma_f32 v[14:15], v[62:63], v[52:53], v[14:15] op_sel_hi:[0,1,1]
	v_fmac_f32_e32 v24, v64, v27
	v_pk_fma_f32 v[20:21], v[64:65], v[30:31], v[20:21] op_sel_hi:[0,1,1]
	v_pk_fma_f32 v[18:19], v[64:65], v[38:39], v[18:19] op_sel_hi:[0,1,1]
	v_pk_fma_f32 v[16:17], v[64:65], v[46:47], v[16:17] op_sel_hi:[0,1,1]
	v_pk_fma_f32 v[14:15], v[64:65], v[58:59], v[14:15] op_sel_hi:[0,1,1]
	v_fmac_f32_e32 v24, v66, v28
	v_pk_fma_f32 v[20:21], v[66:67], v[34:35], v[20:21] op_sel_hi:[0,1,1]
	v_pk_fma_f32 v[18:19], v[66:67], v[42:43], v[18:19] op_sel_hi:[0,1,1]
	v_pk_fma_f32 v[16:17], v[66:67], v[50:51], v[16:17] op_sel_hi:[0,1,1]
	v_pk_fma_f32 v[14:15], v[66:67], v[54:55], v[14:15] op_sel_hi:[0,1,1]
	v_fmac_f32_e32 v24, v68, v29
	v_pk_fma_f32 v[20:21], v[68:69], v[32:33], v[20:21] op_sel_hi:[0,1,1]
	v_pk_fma_f32 v[18:19], v[68:69], v[40:41], v[18:19] op_sel_hi:[0,1,1]
	v_pk_fma_f32 v[16:17], v[68:69], v[48:49], v[16:17] op_sel_hi:[0,1,1]
	v_pk_fma_f32 v[14:15], v[68:69], v[60:61], v[14:15] op_sel_hi:[0,1,1]
	v_lshl_add_u64 v[132:133], v[22:23], 0, s[16:17]
	v_lshl_add_u64 v[134:135], v[132:133], 0, s[18:19]
	v_lshl_add_u64 v[136:137], v[132:133], 0, s[20:21]
	v_lshl_add_u64 v[138:139], v[132:133], 0, s[34:35]
	global_load_dword v100, v[132:133], off
	global_load_dword v101, v[134:135], off
	global_load_dword v102, v[136:137], off
	global_load_dword v103, v[138:139], off
	s_add_u32 s16, s16, 0x24000
	s_cmp_eq_u32 s16, 0x480000
	s_cselect_b32 s16, 0, s16
	ds_read_b128 v[26:29], v11 offset:4096
	ds_read_b128 v[30:33], v11 offset:8192
	ds_read_b128 v[34:37], v11 offset:12288
	ds_read_b128 v[38:41], v11 offset:16384
	ds_read_b128 v[42:45], v11 offset:20480
	ds_read_b128 v[46:49], v11 offset:24576
	ds_read_b128 v[50:53], v11 offset:28672
	ds_read_b128 v[54:57], v11
	ds_read_b128 v[58:61], v11 offset:32768
	s_waitcnt lgkmcnt(0)
	v_mov_b32_e32 v70, v34
	v_mov_b32_e32 v71, v30
	v_mov_b32_e32 v30, v35
	v_mov_b32_e32 v34, v36
	v_mov_b32_e32 v35, v32
	v_mov_b32_e32 v32, v37
	v_mov_b32_e32 v36, v42
	v_mov_b32_e32 v37, v38
	v_mov_b32_e32 v38, v43
	v_mov_b32_e32 v42, v44
	v_mov_b32_e32 v43, v40
	v_mov_b32_e32 v40, v45
	v_mov_b32_e32 v44, v50
	v_mov_b32_e32 v45, v46
	v_mov_b32_e32 v46, v51
	v_mov_b32_e32 v50, v52
	v_mov_b32_e32 v51, v48
	v_mov_b32_e32 v48, v53
	v_mov_b32_e32 v52, v54
	v_mov_b32_e32 v53, v58
	v_mov_b32_e32 v58, v55
	v_mov_b32_e32 v54, v56
	v_mov_b32_e32 v55, v60
	v_mov_b32_e32 v60, v57
	v_add_u32_e32 v11, 16, v11
	s_waitcnt vmcnt(28)
	v_mov_b32_e32 v62, v104
	v_mov_b32_e32 v64, v105
	v_mov_b32_e32 v66, v106
	v_mov_b32_e32 v68, v107
	v_fmac_f32_e32 v24, v62, v26
	v_pk_fma_f32 v[20:21], v[62:63], v[70:71], v[20:21] op_sel_hi:[0,1,1]
	v_pk_fma_f32 v[18:19], v[62:63], v[36:37], v[18:19] op_sel_hi:[0,1,1]
	v_pk_fma_f32 v[16:17], v[62:63], v[44:45], v[16:17] op_sel_hi:[0,1,1]
	v_pk_fma_f32 v[14:15], v[62:63], v[52:53], v[14:15] op_sel_hi:[0,1,1]
	v_fmac_f32_e32 v24, v64, v27
	v_pk_fma_f32 v[20:21], v[64:65], v[30:31], v[20:21] op_sel_hi:[0,1,1]
	v_pk_fma_f32 v[18:19], v[64:65], v[38:39], v[18:19] op_sel_hi:[0,1,1]
	v_pk_fma_f32 v[16:17], v[64:65], v[46:47], v[16:17] op_sel_hi:[0,1,1]
	v_pk_fma_f32 v[14:15], v[64:65], v[58:59], v[14:15] op_sel_hi:[0,1,1]
	v_fmac_f32_e32 v24, v66, v28
	v_pk_fma_f32 v[20:21], v[66:67], v[34:35], v[20:21] op_sel_hi:[0,1,1]
	v_pk_fma_f32 v[18:19], v[66:67], v[42:43], v[18:19] op_sel_hi:[0,1,1]
	v_pk_fma_f32 v[16:17], v[66:67], v[50:51], v[16:17] op_sel_hi:[0,1,1]
	v_pk_fma_f32 v[14:15], v[66:67], v[54:55], v[14:15] op_sel_hi:[0,1,1]
	v_fmac_f32_e32 v24, v68, v29
	v_pk_fma_f32 v[20:21], v[68:69], v[32:33], v[20:21] op_sel_hi:[0,1,1]
	v_pk_fma_f32 v[18:19], v[68:69], v[40:41], v[18:19] op_sel_hi:[0,1,1]
	v_pk_fma_f32 v[16:17], v[68:69], v[48:49], v[16:17] op_sel_hi:[0,1,1]
	v_pk_fma_f32 v[14:15], v[68:69], v[60:61], v[14:15] op_sel_hi:[0,1,1]
	v_lshl_add_u64 v[132:133], v[22:23], 0, s[16:17]
	v_lshl_add_u64 v[134:135], v[132:133], 0, s[18:19]
	v_lshl_add_u64 v[136:137], v[132:133], 0, s[20:21]
	v_lshl_add_u64 v[138:139], v[132:133], 0, s[34:35]
	global_load_dword v104, v[132:133], off
	global_load_dword v105, v[134:135], off
	global_load_dword v106, v[136:137], off
	global_load_dword v107, v[138:139], off
	s_add_u32 s16, s16, 0x24000
	s_cmp_eq_u32 s16, 0x480000
	s_cselect_b32 s16, 0, s16
	ds_read_b128 v[26:29], v11 offset:4096
	ds_read_b128 v[30:33], v11 offset:8192
	ds_read_b128 v[34:37], v11 offset:12288
	ds_read_b128 v[38:41], v11 offset:16384
	ds_read_b128 v[42:45], v11 offset:20480
	ds_read_b128 v[46:49], v11 offset:24576
	ds_read_b128 v[50:53], v11 offset:28672
	ds_read_b128 v[54:57], v11
	ds_read_b128 v[58:61], v11 offset:32768
	s_waitcnt lgkmcnt(0)
	v_mov_b32_e32 v70, v34
	v_mov_b32_e32 v71, v30
	v_mov_b32_e32 v30, v35
	v_mov_b32_e32 v34, v36
	v_mov_b32_e32 v35, v32
	v_mov_b32_e32 v32, v37
	v_mov_b32_e32 v36, v42
	v_mov_b32_e32 v37, v38
	v_mov_b32_e32 v38, v43
	v_mov_b32_e32 v42, v44
	v_mov_b32_e32 v43, v40
	v_mov_b32_e32 v40, v45
	v_mov_b32_e32 v44, v50
	v_mov_b32_e32 v45, v46
	v_mov_b32_e32 v46, v51
	v_mov_b32_e32 v50, v52
	v_mov_b32_e32 v51, v48
	v_mov_b32_e32 v48, v53
	v_mov_b32_e32 v52, v54
	v_mov_b32_e32 v53, v58
	v_mov_b32_e32 v58, v55
	v_mov_b32_e32 v54, v56
	v_mov_b32_e32 v55, v60
	v_mov_b32_e32 v60, v57
	v_add_u32_e32 v11, 16, v11
	s_waitcnt vmcnt(28)
	v_mov_b32_e32 v62, v108
	v_mov_b32_e32 v64, v109
	v_mov_b32_e32 v66, v110
	v_mov_b32_e32 v68, v111
	v_fmac_f32_e32 v24, v62, v26
	v_pk_fma_f32 v[20:21], v[62:63], v[70:71], v[20:21] op_sel_hi:[0,1,1]
	v_pk_fma_f32 v[18:19], v[62:63], v[36:37], v[18:19] op_sel_hi:[0,1,1]
	v_pk_fma_f32 v[16:17], v[62:63], v[44:45], v[16:17] op_sel_hi:[0,1,1]
	v_pk_fma_f32 v[14:15], v[62:63], v[52:53], v[14:15] op_sel_hi:[0,1,1]
	v_fmac_f32_e32 v24, v64, v27
	v_pk_fma_f32 v[20:21], v[64:65], v[30:31], v[20:21] op_sel_hi:[0,1,1]
	v_pk_fma_f32 v[18:19], v[64:65], v[38:39], v[18:19] op_sel_hi:[0,1,1]
	v_pk_fma_f32 v[16:17], v[64:65], v[46:47], v[16:17] op_sel_hi:[0,1,1]
	v_pk_fma_f32 v[14:15], v[64:65], v[58:59], v[14:15] op_sel_hi:[0,1,1]
	v_fmac_f32_e32 v24, v66, v28
	v_pk_fma_f32 v[20:21], v[66:67], v[34:35], v[20:21] op_sel_hi:[0,1,1]
	v_pk_fma_f32 v[18:19], v[66:67], v[42:43], v[18:19] op_sel_hi:[0,1,1]
	v_pk_fma_f32 v[16:17], v[66:67], v[50:51], v[16:17] op_sel_hi:[0,1,1]
	v_pk_fma_f32 v[14:15], v[66:67], v[54:55], v[14:15] op_sel_hi:[0,1,1]
	v_fmac_f32_e32 v24, v68, v29
	v_pk_fma_f32 v[20:21], v[68:69], v[32:33], v[20:21] op_sel_hi:[0,1,1]
	v_pk_fma_f32 v[18:19], v[68:69], v[40:41], v[18:19] op_sel_hi:[0,1,1]
	v_pk_fma_f32 v[16:17], v[68:69], v[48:49], v[16:17] op_sel_hi:[0,1,1]
	v_pk_fma_f32 v[14:15], v[68:69], v[60:61], v[14:15] op_sel_hi:[0,1,1]
	v_lshl_add_u64 v[132:133], v[22:23], 0, s[16:17]
	v_lshl_add_u64 v[134:135], v[132:133], 0, s[18:19]
	v_lshl_add_u64 v[136:137], v[132:133], 0, s[20:21]
	v_lshl_add_u64 v[138:139], v[132:133], 0, s[34:35]
	global_load_dword v108, v[132:133], off
	global_load_dword v109, v[134:135], off
	global_load_dword v110, v[136:137], off
	global_load_dword v111, v[138:139], off
	s_add_u32 s16, s16, 0x24000
	s_cmp_eq_u32 s16, 0x480000
	s_cselect_b32 s16, 0, s16
	ds_read_b128 v[26:29], v11 offset:4096
	ds_read_b128 v[30:33], v11 offset:8192
	ds_read_b128 v[34:37], v11 offset:12288
	ds_read_b128 v[38:41], v11 offset:16384
	ds_read_b128 v[42:45], v11 offset:20480
	ds_read_b128 v[46:49], v11 offset:24576
	ds_read_b128 v[50:53], v11 offset:28672
	ds_read_b128 v[54:57], v11
	ds_read_b128 v[58:61], v11 offset:32768
	s_waitcnt lgkmcnt(0)
	v_mov_b32_e32 v70, v34
	v_mov_b32_e32 v71, v30
	v_mov_b32_e32 v30, v35
	v_mov_b32_e32 v34, v36
	v_mov_b32_e32 v35, v32
	v_mov_b32_e32 v32, v37
	v_mov_b32_e32 v36, v42
	v_mov_b32_e32 v37, v38
	v_mov_b32_e32 v38, v43
	v_mov_b32_e32 v42, v44
	v_mov_b32_e32 v43, v40
	v_mov_b32_e32 v40, v45
	v_mov_b32_e32 v44, v50
	v_mov_b32_e32 v45, v46
	v_mov_b32_e32 v46, v51
	v_mov_b32_e32 v50, v52
	v_mov_b32_e32 v51, v48
	v_mov_b32_e32 v48, v53
	v_mov_b32_e32 v52, v54
	v_mov_b32_e32 v53, v58
	v_mov_b32_e32 v58, v55
	v_mov_b32_e32 v54, v56
	v_mov_b32_e32 v55, v60
	v_mov_b32_e32 v60, v57
	v_add_u32_e32 v11, 16, v11
	s_waitcnt vmcnt(28)
	v_mov_b32_e32 v62, v112
	v_mov_b32_e32 v64, v113
	v_mov_b32_e32 v66, v114
	v_mov_b32_e32 v68, v115
	v_fmac_f32_e32 v24, v62, v26
	v_pk_fma_f32 v[20:21], v[62:63], v[70:71], v[20:21] op_sel_hi:[0,1,1]
	v_pk_fma_f32 v[18:19], v[62:63], v[36:37], v[18:19] op_sel_hi:[0,1,1]
	v_pk_fma_f32 v[16:17], v[62:63], v[44:45], v[16:17] op_sel_hi:[0,1,1]
	v_pk_fma_f32 v[14:15], v[62:63], v[52:53], v[14:15] op_sel_hi:[0,1,1]
	v_fmac_f32_e32 v24, v64, v27
	v_pk_fma_f32 v[20:21], v[64:65], v[30:31], v[20:21] op_sel_hi:[0,1,1]
	v_pk_fma_f32 v[18:19], v[64:65], v[38:39], v[18:19] op_sel_hi:[0,1,1]
	v_pk_fma_f32 v[16:17], v[64:65], v[46:47], v[16:17] op_sel_hi:[0,1,1]
	v_pk_fma_f32 v[14:15], v[64:65], v[58:59], v[14:15] op_sel_hi:[0,1,1]
	v_fmac_f32_e32 v24, v66, v28
	v_pk_fma_f32 v[20:21], v[66:67], v[34:35], v[20:21] op_sel_hi:[0,1,1]
	v_pk_fma_f32 v[18:19], v[66:67], v[42:43], v[18:19] op_sel_hi:[0,1,1]
	v_pk_fma_f32 v[16:17], v[66:67], v[50:51], v[16:17] op_sel_hi:[0,1,1]
	v_pk_fma_f32 v[14:15], v[66:67], v[54:55], v[14:15] op_sel_hi:[0,1,1]
	v_fmac_f32_e32 v24, v68, v29
	v_pk_fma_f32 v[20:21], v[68:69], v[32:33], v[20:21] op_sel_hi:[0,1,1]
	v_pk_fma_f32 v[18:19], v[68:69], v[40:41], v[18:19] op_sel_hi:[0,1,1]
	v_pk_fma_f32 v[16:17], v[68:69], v[48:49], v[16:17] op_sel_hi:[0,1,1]
	v_pk_fma_f32 v[14:15], v[68:69], v[60:61], v[14:15] op_sel_hi:[0,1,1]
	v_lshl_add_u64 v[132:133], v[22:23], 0, s[16:17]
	v_lshl_add_u64 v[134:135], v[132:133], 0, s[18:19]
	v_lshl_add_u64 v[136:137], v[132:133], 0, s[20:21]
	v_lshl_add_u64 v[138:139], v[132:133], 0, s[34:35]
	global_load_dword v112, v[132:133], off
	global_load_dword v113, v[134:135], off
	global_load_dword v114, v[136:137], off
	global_load_dword v115, v[138:139], off
	s_add_u32 s16, s16, 0x24000
	s_cmp_eq_u32 s16, 0x480000
	s_cselect_b32 s16, 0, s16
	ds_read_b128 v[26:29], v11 offset:4096
	ds_read_b128 v[30:33], v11 offset:8192
	ds_read_b128 v[34:37], v11 offset:12288
	ds_read_b128 v[38:41], v11 offset:16384
	ds_read_b128 v[42:45], v11 offset:20480
	ds_read_b128 v[46:49], v11 offset:24576
	ds_read_b128 v[50:53], v11 offset:28672
	ds_read_b128 v[54:57], v11
	ds_read_b128 v[58:61], v11 offset:32768
	s_waitcnt lgkmcnt(0)
	v_mov_b32_e32 v70, v34
	v_mov_b32_e32 v71, v30
	v_mov_b32_e32 v30, v35
	v_mov_b32_e32 v34, v36
	v_mov_b32_e32 v35, v32
	v_mov_b32_e32 v32, v37
	v_mov_b32_e32 v36, v42
	v_mov_b32_e32 v37, v38
	v_mov_b32_e32 v38, v43
	v_mov_b32_e32 v42, v44
	v_mov_b32_e32 v43, v40
	v_mov_b32_e32 v40, v45
	v_mov_b32_e32 v44, v50
	v_mov_b32_e32 v45, v46
	v_mov_b32_e32 v46, v51
	v_mov_b32_e32 v50, v52
	v_mov_b32_e32 v51, v48
	v_mov_b32_e32 v48, v53
	v_mov_b32_e32 v52, v54
	v_mov_b32_e32 v53, v58
	v_mov_b32_e32 v58, v55
	v_mov_b32_e32 v54, v56
	v_mov_b32_e32 v55, v60
	v_mov_b32_e32 v60, v57
	v_add_u32_e32 v11, 16, v11
	s_waitcnt vmcnt(28)
	v_mov_b32_e32 v62, v116
	v_mov_b32_e32 v64, v117
	v_mov_b32_e32 v66, v118
	v_mov_b32_e32 v68, v119
	v_fmac_f32_e32 v24, v62, v26
	v_pk_fma_f32 v[20:21], v[62:63], v[70:71], v[20:21] op_sel_hi:[0,1,1]
	v_pk_fma_f32 v[18:19], v[62:63], v[36:37], v[18:19] op_sel_hi:[0,1,1]
	v_pk_fma_f32 v[16:17], v[62:63], v[44:45], v[16:17] op_sel_hi:[0,1,1]
	v_pk_fma_f32 v[14:15], v[62:63], v[52:53], v[14:15] op_sel_hi:[0,1,1]
	v_fmac_f32_e32 v24, v64, v27
	v_pk_fma_f32 v[20:21], v[64:65], v[30:31], v[20:21] op_sel_hi:[0,1,1]
	v_pk_fma_f32 v[18:19], v[64:65], v[38:39], v[18:19] op_sel_hi:[0,1,1]
	v_pk_fma_f32 v[16:17], v[64:65], v[46:47], v[16:17] op_sel_hi:[0,1,1]
	v_pk_fma_f32 v[14:15], v[64:65], v[58:59], v[14:15] op_sel_hi:[0,1,1]
	v_fmac_f32_e32 v24, v66, v28
	v_pk_fma_f32 v[20:21], v[66:67], v[34:35], v[20:21] op_sel_hi:[0,1,1]
	v_pk_fma_f32 v[18:19], v[66:67], v[42:43], v[18:19] op_sel_hi:[0,1,1]
	v_pk_fma_f32 v[16:17], v[66:67], v[50:51], v[16:17] op_sel_hi:[0,1,1]
	v_pk_fma_f32 v[14:15], v[66:67], v[54:55], v[14:15] op_sel_hi:[0,1,1]
	v_fmac_f32_e32 v24, v68, v29
	v_pk_fma_f32 v[20:21], v[68:69], v[32:33], v[20:21] op_sel_hi:[0,1,1]
	v_pk_fma_f32 v[18:19], v[68:69], v[40:41], v[18:19] op_sel_hi:[0,1,1]
	v_pk_fma_f32 v[16:17], v[68:69], v[48:49], v[16:17] op_sel_hi:[0,1,1]
	v_pk_fma_f32 v[14:15], v[68:69], v[60:61], v[14:15] op_sel_hi:[0,1,1]
	v_lshl_add_u64 v[132:133], v[22:23], 0, s[16:17]
	v_lshl_add_u64 v[134:135], v[132:133], 0, s[18:19]
	v_lshl_add_u64 v[136:137], v[132:133], 0, s[20:21]
	v_lshl_add_u64 v[138:139], v[132:133], 0, s[34:35]
	global_load_dword v116, v[132:133], off
	global_load_dword v117, v[134:135], off
	global_load_dword v118, v[136:137], off
	global_load_dword v119, v[138:139], off
	s_add_u32 s16, s16, 0x24000
	s_cmp_eq_u32 s16, 0x480000
	s_cselect_b32 s16, 0, s16
	ds_read_b128 v[26:29], v11 offset:4096
	ds_read_b128 v[30:33], v11 offset:8192
	ds_read_b128 v[34:37], v11 offset:12288
	ds_read_b128 v[38:41], v11 offset:16384
	ds_read_b128 v[42:45], v11 offset:20480
	ds_read_b128 v[46:49], v11 offset:24576
	ds_read_b128 v[50:53], v11 offset:28672
	ds_read_b128 v[54:57], v11
	ds_read_b128 v[58:61], v11 offset:32768
	s_waitcnt lgkmcnt(0)
	v_mov_b32_e32 v70, v34
	v_mov_b32_e32 v71, v30
	v_mov_b32_e32 v30, v35
	v_mov_b32_e32 v34, v36
	v_mov_b32_e32 v35, v32
	v_mov_b32_e32 v32, v37
	v_mov_b32_e32 v36, v42
	v_mov_b32_e32 v37, v38
	v_mov_b32_e32 v38, v43
	v_mov_b32_e32 v42, v44
	v_mov_b32_e32 v43, v40
	v_mov_b32_e32 v40, v45
	v_mov_b32_e32 v44, v50
	v_mov_b32_e32 v45, v46
	v_mov_b32_e32 v46, v51
	v_mov_b32_e32 v50, v52
	v_mov_b32_e32 v51, v48
	v_mov_b32_e32 v48, v53
	v_mov_b32_e32 v52, v54
	v_mov_b32_e32 v53, v58
	v_mov_b32_e32 v58, v55
	v_mov_b32_e32 v54, v56
	v_mov_b32_e32 v55, v60
	v_mov_b32_e32 v60, v57
	v_add_u32_e32 v11, 16, v11
	s_waitcnt vmcnt(28)
	v_mov_b32_e32 v62, v120
	v_mov_b32_e32 v64, v121
	v_mov_b32_e32 v66, v122
	v_mov_b32_e32 v68, v123
	v_fmac_f32_e32 v24, v62, v26
	v_pk_fma_f32 v[20:21], v[62:63], v[70:71], v[20:21] op_sel_hi:[0,1,1]
	v_pk_fma_f32 v[18:19], v[62:63], v[36:37], v[18:19] op_sel_hi:[0,1,1]
	v_pk_fma_f32 v[16:17], v[62:63], v[44:45], v[16:17] op_sel_hi:[0,1,1]
	v_pk_fma_f32 v[14:15], v[62:63], v[52:53], v[14:15] op_sel_hi:[0,1,1]
	v_fmac_f32_e32 v24, v64, v27
	v_pk_fma_f32 v[20:21], v[64:65], v[30:31], v[20:21] op_sel_hi:[0,1,1]
	v_pk_fma_f32 v[18:19], v[64:65], v[38:39], v[18:19] op_sel_hi:[0,1,1]
	v_pk_fma_f32 v[16:17], v[64:65], v[46:47], v[16:17] op_sel_hi:[0,1,1]
	v_pk_fma_f32 v[14:15], v[64:65], v[58:59], v[14:15] op_sel_hi:[0,1,1]
	v_fmac_f32_e32 v24, v66, v28
	v_pk_fma_f32 v[20:21], v[66:67], v[34:35], v[20:21] op_sel_hi:[0,1,1]
	v_pk_fma_f32 v[18:19], v[66:67], v[42:43], v[18:19] op_sel_hi:[0,1,1]
	v_pk_fma_f32 v[16:17], v[66:67], v[50:51], v[16:17] op_sel_hi:[0,1,1]
	v_pk_fma_f32 v[14:15], v[66:67], v[54:55], v[14:15] op_sel_hi:[0,1,1]
	v_fmac_f32_e32 v24, v68, v29
	v_pk_fma_f32 v[20:21], v[68:69], v[32:33], v[20:21] op_sel_hi:[0,1,1]
	v_pk_fma_f32 v[18:19], v[68:69], v[40:41], v[18:19] op_sel_hi:[0,1,1]
	v_pk_fma_f32 v[16:17], v[68:69], v[48:49], v[16:17] op_sel_hi:[0,1,1]
	v_pk_fma_f32 v[14:15], v[68:69], v[60:61], v[14:15] op_sel_hi:[0,1,1]
	v_lshl_add_u64 v[132:133], v[22:23], 0, s[16:17]
	v_lshl_add_u64 v[134:135], v[132:133], 0, s[18:19]
	v_lshl_add_u64 v[136:137], v[132:133], 0, s[20:21]
	v_lshl_add_u64 v[138:139], v[132:133], 0, s[34:35]
	global_load_dword v120, v[132:133], off
	global_load_dword v121, v[134:135], off
	global_load_dword v122, v[136:137], off
	global_load_dword v123, v[138:139], off
	s_add_u32 s16, s16, 0x24000
	s_cmp_eq_u32 s16, 0x480000
	s_cselect_b32 s16, 0, s16
	ds_read_b128 v[26:29], v11 offset:4096
	ds_read_b128 v[30:33], v11 offset:8192
	ds_read_b128 v[34:37], v11 offset:12288
	ds_read_b128 v[38:41], v11 offset:16384
	ds_read_b128 v[42:45], v11 offset:20480
	ds_read_b128 v[46:49], v11 offset:24576
	ds_read_b128 v[50:53], v11 offset:28672
	ds_read_b128 v[54:57], v11
	ds_read_b128 v[58:61], v11 offset:32768
	s_waitcnt lgkmcnt(0)
	v_mov_b32_e32 v70, v34
	v_mov_b32_e32 v71, v30
	v_mov_b32_e32 v30, v35
	v_mov_b32_e32 v34, v36
	v_mov_b32_e32 v35, v32
	v_mov_b32_e32 v32, v37
	v_mov_b32_e32 v36, v42
	v_mov_b32_e32 v37, v38
	v_mov_b32_e32 v38, v43
	v_mov_b32_e32 v42, v44
	v_mov_b32_e32 v43, v40
	v_mov_b32_e32 v40, v45
	v_mov_b32_e32 v44, v50
	v_mov_b32_e32 v45, v46
	v_mov_b32_e32 v46, v51
	v_mov_b32_e32 v50, v52
	v_mov_b32_e32 v51, v48
	v_mov_b32_e32 v48, v53
	v_mov_b32_e32 v52, v54
	v_mov_b32_e32 v53, v58
	v_mov_b32_e32 v58, v55
	v_mov_b32_e32 v54, v56
	v_mov_b32_e32 v55, v60
	v_mov_b32_e32 v60, v57
	v_add_u32_e32 v11, 16, v11
	s_waitcnt vmcnt(28)
	v_mov_b32_e32 v62, v124
	v_mov_b32_e32 v64, v125
	v_mov_b32_e32 v66, v126
	v_mov_b32_e32 v68, v127
	v_fmac_f32_e32 v24, v62, v26
	v_pk_fma_f32 v[20:21], v[62:63], v[70:71], v[20:21] op_sel_hi:[0,1,1]
	v_pk_fma_f32 v[18:19], v[62:63], v[36:37], v[18:19] op_sel_hi:[0,1,1]
	v_pk_fma_f32 v[16:17], v[62:63], v[44:45], v[16:17] op_sel_hi:[0,1,1]
	v_pk_fma_f32 v[14:15], v[62:63], v[52:53], v[14:15] op_sel_hi:[0,1,1]
	v_fmac_f32_e32 v24, v64, v27
	v_pk_fma_f32 v[20:21], v[64:65], v[30:31], v[20:21] op_sel_hi:[0,1,1]
	v_pk_fma_f32 v[18:19], v[64:65], v[38:39], v[18:19] op_sel_hi:[0,1,1]
	v_pk_fma_f32 v[16:17], v[64:65], v[46:47], v[16:17] op_sel_hi:[0,1,1]
	v_pk_fma_f32 v[14:15], v[64:65], v[58:59], v[14:15] op_sel_hi:[0,1,1]
	v_fmac_f32_e32 v24, v66, v28
	v_pk_fma_f32 v[20:21], v[66:67], v[34:35], v[20:21] op_sel_hi:[0,1,1]
	v_pk_fma_f32 v[18:19], v[66:67], v[42:43], v[18:19] op_sel_hi:[0,1,1]
	v_pk_fma_f32 v[16:17], v[66:67], v[50:51], v[16:17] op_sel_hi:[0,1,1]
	v_pk_fma_f32 v[14:15], v[66:67], v[54:55], v[14:15] op_sel_hi:[0,1,1]
	v_fmac_f32_e32 v24, v68, v29
	v_pk_fma_f32 v[20:21], v[68:69], v[32:33], v[20:21] op_sel_hi:[0,1,1]
	v_pk_fma_f32 v[18:19], v[68:69], v[40:41], v[18:19] op_sel_hi:[0,1,1]
	v_pk_fma_f32 v[16:17], v[68:69], v[48:49], v[16:17] op_sel_hi:[0,1,1]
	v_pk_fma_f32 v[14:15], v[68:69], v[60:61], v[14:15] op_sel_hi:[0,1,1]
	v_lshl_add_u64 v[132:133], v[22:23], 0, s[16:17]
	v_lshl_add_u64 v[134:135], v[132:133], 0, s[18:19]
	v_lshl_add_u64 v[136:137], v[132:133], 0, s[20:21]
	v_lshl_add_u64 v[138:139], v[132:133], 0, s[34:35]
	global_load_dword v124, v[132:133], off
	global_load_dword v125, v[134:135], off
	global_load_dword v126, v[136:137], off
	global_load_dword v127, v[138:139], off
	s_add_u32 s16, s16, 0x24000
	s_cmp_eq_u32 s16, 0x480000
	s_cselect_b32 s16, 0, s16
	ds_read_b128 v[26:29], v11 offset:4096
	ds_read_b128 v[30:33], v11 offset:8192
	ds_read_b128 v[34:37], v11 offset:12288
	ds_read_b128 v[38:41], v11 offset:16384
	ds_read_b128 v[42:45], v11 offset:20480
	ds_read_b128 v[46:49], v11 offset:24576
	ds_read_b128 v[50:53], v11 offset:28672
	ds_read_b128 v[54:57], v11
	ds_read_b128 v[58:61], v11 offset:32768
	s_waitcnt lgkmcnt(0)
	v_mov_b32_e32 v70, v34
	v_mov_b32_e32 v71, v30
	v_mov_b32_e32 v30, v35
	v_mov_b32_e32 v34, v36
	v_mov_b32_e32 v35, v32
	v_mov_b32_e32 v32, v37
	v_mov_b32_e32 v36, v42
	v_mov_b32_e32 v37, v38
	v_mov_b32_e32 v38, v43
	v_mov_b32_e32 v42, v44
	v_mov_b32_e32 v43, v40
	v_mov_b32_e32 v40, v45
	v_mov_b32_e32 v44, v50
	v_mov_b32_e32 v45, v46
	v_mov_b32_e32 v46, v51
	v_mov_b32_e32 v50, v52
	v_mov_b32_e32 v51, v48
	v_mov_b32_e32 v48, v53
	v_mov_b32_e32 v52, v54
	v_mov_b32_e32 v53, v58
	v_mov_b32_e32 v58, v55
	v_mov_b32_e32 v54, v56
	v_mov_b32_e32 v55, v60
	v_mov_b32_e32 v60, v57
	v_add_u32_e32 v11, 16, v11
	s_waitcnt vmcnt(28)
	v_mov_b32_e32 v62, v128
	v_mov_b32_e32 v64, v129
	v_mov_b32_e32 v66, v130
	v_mov_b32_e32 v68, v131
	v_fmac_f32_e32 v24, v62, v26
	v_pk_fma_f32 v[20:21], v[62:63], v[70:71], v[20:21] op_sel_hi:[0,1,1]
	v_pk_fma_f32 v[18:19], v[62:63], v[36:37], v[18:19] op_sel_hi:[0,1,1]
	v_pk_fma_f32 v[16:17], v[62:63], v[44:45], v[16:17] op_sel_hi:[0,1,1]
	v_pk_fma_f32 v[14:15], v[62:63], v[52:53], v[14:15] op_sel_hi:[0,1,1]
	v_fmac_f32_e32 v24, v64, v27
	v_pk_fma_f32 v[20:21], v[64:65], v[30:31], v[20:21] op_sel_hi:[0,1,1]
	v_pk_fma_f32 v[18:19], v[64:65], v[38:39], v[18:19] op_sel_hi:[0,1,1]
	v_pk_fma_f32 v[16:17], v[64:65], v[46:47], v[16:17] op_sel_hi:[0,1,1]
	v_pk_fma_f32 v[14:15], v[64:65], v[58:59], v[14:15] op_sel_hi:[0,1,1]
	v_fmac_f32_e32 v24, v66, v28
	v_pk_fma_f32 v[20:21], v[66:67], v[34:35], v[20:21] op_sel_hi:[0,1,1]
	v_pk_fma_f32 v[18:19], v[66:67], v[42:43], v[18:19] op_sel_hi:[0,1,1]
	v_pk_fma_f32 v[16:17], v[66:67], v[50:51], v[16:17] op_sel_hi:[0,1,1]
	v_pk_fma_f32 v[14:15], v[66:67], v[54:55], v[14:15] op_sel_hi:[0,1,1]
	v_fmac_f32_e32 v24, v68, v29
	v_pk_fma_f32 v[20:21], v[68:69], v[32:33], v[20:21] op_sel_hi:[0,1,1]
	v_pk_fma_f32 v[18:19], v[68:69], v[40:41], v[18:19] op_sel_hi:[0,1,1]
	v_pk_fma_f32 v[16:17], v[68:69], v[48:49], v[16:17] op_sel_hi:[0,1,1]
	v_pk_fma_f32 v[14:15], v[68:69], v[60:61], v[14:15] op_sel_hi:[0,1,1]
	v_lshl_add_u64 v[132:133], v[22:23], 0, s[16:17]
	v_lshl_add_u64 v[134:135], v[132:133], 0, s[18:19]
	v_lshl_add_u64 v[136:137], v[132:133], 0, s[20:21]
	v_lshl_add_u64 v[138:139], v[132:133], 0, s[34:35]
	global_load_dword v128, v[132:133], off
	global_load_dword v129, v[134:135], off
	global_load_dword v130, v[136:137], off
	global_load_dword v131, v[138:139], off
	s_add_u32 s16, s16, 0x24000
	s_cmp_eq_u32 s16, 0x480000
	s_cselect_b32 s16, 0, s16
	s_sub_u32 s38, s38, 1
	s_cmp_lg_u32 s38, 0
	s_cbranch_scc1 .Lpm_loop
	s_waitcnt vmcnt(0)
	ds_write2st64_b32 v10, v14, v24 offset0:144 offset1:145
	ds_write2st64_b32 v10, v21, v20 offset0:146 offset1:147
	ds_write2st64_b32 v10, v19, v18 offset0:148 offset1:149
	ds_write2st64_b32 v10, v17, v16 offset0:150 offset1:151
	ds_write_b32 v10, v15 offset:38912
	s_waitcnt lgkmcnt(0)
	s_barrier
	s_and_saveexec_b64 s[8:9], vcc
	s_cbranch_execz .LBB0_13
	s_mul_i32 s3, s6, 0x2400
	s_add_i32 s4, s3, s2
	s_ashr_i32 s3, s2, 31
	v_or_b32_e32 v14, s4, v1
	s_mul_i32 s6, s6, 9
	v_ashrrev_i32_e32 v15, 31, v14
	v_lshl_add_u64 v[16:17], s[2:3], 2, v[12:13]
	s_mov_b64 s[2:3], 0
	v_mov_b32_e32 v11, v2
